# dropped the full vmcnt drain between a tile epilogue and the next tile K loop (covered by the loop own counted waits)
# speedup vs baseline: 1.0428x; 1.0041x over previous
.Llora_n:
	s_add_u32 s10, s78, 0x80
	s_addc_u32 s11, s79, 0
	s_add_u32 s84, s84, 0x100
	v_mov_b32_e32 v0, 0
	s_addc_u32 s85, s85, 0
	s_mov_b32 s78, 0
	v_mov_b32_e32 v1, v0
	v_mov_b32_e32 v2, v0
	v_mov_b32_e32 v3, v0
	v_mov_b32_e32 v8, v0
	v_mov_b32_e32 v9, v0
	v_mov_b32_e32 v10, v0
	v_mov_b32_e32 v11, v0
	v_mov_b32_e32 v4, v0
	v_mov_b32_e32 v5, v0
	v_mov_b32_e32 v6, v0
	v_mov_b32_e32 v7, v0
	v_mov_b32_e32 v12, v0
	v_mov_b32_e32 v13, v0
	v_mov_b32_e32 v14, v0
	v_mov_b32_e32 v15, v0
	v_mov_b32_e32 v32, v0
	v_mov_b32_e32 v33, v0
	v_mov_b32_e32 v34, v0
	v_mov_b32_e32 v35, v0
	v_mov_b32_e32 v40, v0
	v_mov_b32_e32 v41, v0
	v_mov_b32_e32 v42, v0
	v_mov_b32_e32 v43, v0
	v_mov_b32_e32 v36, v0
	v_mov_b32_e32 v37, v0
	v_mov_b32_e32 v38, v0
	v_mov_b32_e32 v39, v0
	v_mov_b32_e32 v44, v0
	v_mov_b32_e32 v45, v0
	v_mov_b32_e32 v46, v0
	v_mov_b32_e32 v47, v0
	v_mov_b32_e32 v16, v0
	v_mov_b32_e32 v17, v0
	v_mov_b32_e32 v18, v0
	v_mov_b32_e32 v19, v0
	v_mov_b32_e32 v24, v0
	v_mov_b32_e32 v25, v0
	v_mov_b32_e32 v26, v0
	v_mov_b32_e32 v27, v0
	v_mov_b32_e32 v20, v0
	v_mov_b32_e32 v21, v0
	v_mov_b32_e32 v22, v0
	v_mov_b32_e32 v23, v0
	v_mov_b32_e32 v28, v0
	v_mov_b32_e32 v29, v0
	v_mov_b32_e32 v30, v0
	v_mov_b32_e32 v31, v0
	v_mov_b32_e32 v48, v0
	v_mov_b32_e32 v49, v0
	v_mov_b32_e32 v50, v0
	v_mov_b32_e32 v51, v0
	v_mov_b32_e32 v52, v0
	v_mov_b32_e32 v53, v0
	v_mov_b32_e32 v54, v0
	v_mov_b32_e32 v55, v0
	v_mov_b32_e32 v56, v0
	v_mov_b32_e32 v57, v0
	v_mov_b32_e32 v58, v0
	v_mov_b32_e32 v59, v0
	v_mov_b32_e32 v60, v0
	v_mov_b32_e32 v61, v0
	v_mov_b32_e32 v62, v0
	v_mov_b32_e32 v63, v0
	v_mov_b32_e32 v64, v0
	v_mov_b32_e32 v65, v0
	v_mov_b32_e32 v66, v0
	v_mov_b32_e32 v67, v0
	v_mov_b32_e32 v72, v0
	v_mov_b32_e32 v73, v0
	v_mov_b32_e32 v74, v0
	v_mov_b32_e32 v75, v0
	v_mov_b32_e32 v68, v0
	v_mov_b32_e32 v69, v0
	v_mov_b32_e32 v70, v0
	v_mov_b32_e32 v71, v0
	v_mov_b32_e32 v76, v0
	v_mov_b32_e32 v77, v0
	v_mov_b32_e32 v78, v0
	v_mov_b32_e32 v79, v0
	v_mov_b32_e32 v96, v0
	v_mov_b32_e32 v97, v0
	v_mov_b32_e32 v98, v0
	v_mov_b32_e32 v99, v0
	v_mov_b32_e32 v104, v0
	v_mov_b32_e32 v105, v0
	v_mov_b32_e32 v106, v0
	v_mov_b32_e32 v107, v0
	v_mov_b32_e32 v100, v0
	v_mov_b32_e32 v101, v0
	v_mov_b32_e32 v102, v0
	v_mov_b32_e32 v103, v0
	v_mov_b32_e32 v108, v0
	v_mov_b32_e32 v109, v0
	v_mov_b32_e32 v110, v0
	v_mov_b32_e32 v111, v0
	v_mov_b32_e32 v80, v0
	v_mov_b32_e32 v81, v0
	v_mov_b32_e32 v82, v0
	v_mov_b32_e32 v83, v0
	v_mov_b32_e32 v88, v0
	v_mov_b32_e32 v89, v0
	v_mov_b32_e32 v90, v0
	v_mov_b32_e32 v91, v0
	v_mov_b32_e32 v84, v0
	v_mov_b32_e32 v85, v0
	v_mov_b32_e32 v86, v0
	v_mov_b32_e32 v87, v0
	v_mov_b32_e32 v92, v0
	v_mov_b32_e32 v93, v0
	v_mov_b32_e32 v94, v0
	v_mov_b32_e32 v95, v0
	v_mov_b32_e32 v112, v0
	v_mov_b32_e32 v113, v0
	v_mov_b32_e32 v114, v0
	v_mov_b32_e32 v115, v0
	v_mov_b32_e32 v120, v0
	v_mov_b32_e32 v121, v0
	v_mov_b32_e32 v122, v0
	v_mov_b32_e32 v123, v0
	v_mov_b32_e32 v116, v0
	v_mov_b32_e32 v117, v0
	v_mov_b32_e32 v118, v0
	v_mov_b32_e32 v119, v0
	v_mov_b32_e32 v124, v0
	v_mov_b32_e32 v125, v0
	v_mov_b32_e32 v126, v0
	v_mov_b32_e32 v127, v0
